# FFN-up tile order: column-major over all 12 row tiles of the XCD (fewer distinct weight rows in flight)
# baseline (speedup 1.0000x reference)
.Lhw_ffnup_dloop:
	s_cmp_ge_u32 s2, s64
	s_cbranch_scc1 .Lhw_ffnup_tail
	s_mul_i32 s14, s2, 5462
	s_lshr_b32 s14, s14, 16
	s_mul_i32 s6, s14, 12
	s_sub_i32 s6, s2, s6
	v_readlane_b32 s13, v246, 16
	s_nop 0
	s_add_i32 s6, s6, s13
	s_lshl_b32 s6, s6, 7
	s_lshl_b32 s14, s14, 8
	s_lshl_b32 vcc_lo, s6, 11
	s_add_u32 s66, s10, vcc_lo
	s_addc_u32 s67, s11, 0
	s_lshl_b32 vcc_lo, s14, 11
	s_add_u32 s12, s0, vcc_lo
	s_addc_u32 s13, s1, 0
	s_add_u32 s62, s12, 0x40000
	s_addc_u32 s63, s13, 0
	s_barrier
	s_add_u32 m0, s65, 0x0
	s_nop 0
	global_load_lds_dwordx4 v160, s[66:67]
	s_add_u32 m0, s65, 0x1000
	s_nop 0
	global_load_lds_dwordx4 v161, s[66:67]
	s_add_u32 m0, s65, 0x2000
	s_nop 0
	global_load_lds_dwordx4 v160, s[12:13]
	s_add_u32 m0, s65, 0x3000
	s_nop 0
	global_load_lds_dwordx4 v161, s[12:13]
	s_add_u32 m0, s65, 0x4000
	s_nop 0
	global_load_lds_dwordx4 v160, s[62:63]
	s_add_u32 m0, s65, 0x5000
	s_nop 0
	global_load_lds_dwordx4 v161, s[62:63]
	s_add_u32 s66, s66, 64
	s_addc_u32 s67, s67, 0
	s_add_u32 s12, s12, 64
	s_addc_u32 s13, s13, 0
	s_add_u32 s62, s62, 64
	s_addc_u32 s63, s63, 0
	s_add_u32 m0, s65, 0x6000
	s_nop 0
	global_load_lds_dwordx4 v160, s[66:67]
	s_add_u32 m0, s65, 0x7000
	s_nop 0
	global_load_lds_dwordx4 v161, s[66:67]
	s_add_u32 m0, s65, 0x8000
	s_nop 0
	global_load_lds_dwordx4 v160, s[12:13]
	s_add_u32 m0, s65, 0x9000
	s_nop 0
	global_load_lds_dwordx4 v161, s[12:13]
	s_add_u32 m0, s65, 0xa000
	s_nop 0
	global_load_lds_dwordx4 v160, s[62:63]
	s_add_u32 m0, s65, 0xb000
	s_nop 0
	global_load_lds_dwordx4 v161, s[62:63]
	s_add_u32 s66, s66, 64
	s_addc_u32 s67, s67, 0
	s_add_u32 s12, s12, 64
	s_addc_u32 s13, s13, 0
	s_add_u32 s62, s62, 64
	s_addc_u32 s63, s63, 0
	s_add_u32 m0, s65, 0xc000
	s_nop 0
	global_load_lds_dwordx4 v160, s[66:67]
	s_add_u32 m0, s65, 0xd000
	s_nop 0
	global_load_lds_dwordx4 v161, s[66:67]
	s_add_u32 m0, s65, 0xe000
	s_nop 0
	global_load_lds_dwordx4 v160, s[12:13]
	s_add_u32 m0, s65, 0xf000
	s_nop 0
	global_load_lds_dwordx4 v161, s[12:13]
	s_add_u32 m0, s65, 0x10000
	s_nop 0
	global_load_lds_dwordx4 v160, s[62:63]
	s_add_u32 m0, s65, 0x11000
	s_nop 0
	global_load_lds_dwordx4 v161, s[62:63]
	s_add_u32 s66, s66, 64
	s_addc_u32 s67, s67, 0
	s_add_u32 s12, s12, 64
	s_addc_u32 s13, s13, 0
	s_add_u32 s62, s62, 64
	s_addc_u32 s63, s63, 0
	v_mov_b32_e32 v2, 0
	v_mov_b32_e32 v3, 0
	v_mov_b32_e32 v4, 0
	v_mov_b32_e32 v5, 0
	v_mov_b32_e32 v6, 0
	v_mov_b32_e32 v7, 0
	v_mov_b32_e32 v8, 0
	v_mov_b32_e32 v9, 0
	v_mov_b32_e32 v10, 0
	v_mov_b32_e32 v11, 0
	v_mov_b32_e32 v12, 0
	v_mov_b32_e32 v13, 0
	v_mov_b32_e32 v14, 0
	v_mov_b32_e32 v15, 0
	v_mov_b32_e32 v16, 0
	v_mov_b32_e32 v17, 0
	v_mov_b32_e32 v18, 0
	v_mov_b32_e32 v19, 0
	v_mov_b32_e32 v20, 0
	v_mov_b32_e32 v21, 0
	v_mov_b32_e32 v22, 0
	v_mov_b32_e32 v23, 0
	v_mov_b32_e32 v24, 0
	v_mov_b32_e32 v25, 0
	v_mov_b32_e32 v26, 0
	v_mov_b32_e32 v27, 0
	v_mov_b32_e32 v28, 0
	v_mov_b32_e32 v29, 0
	v_mov_b32_e32 v30, 0
	v_mov_b32_e32 v31, 0
	v_mov_b32_e32 v32, 0
	v_mov_b32_e32 v33, 0
	v_mov_b32_e32 v34, 0
	v_mov_b32_e32 v35, 0
	v_mov_b32_e32 v36, 0
	v_mov_b32_e32 v37, 0
	v_mov_b32_e32 v38, 0
	v_mov_b32_e32 v39, 0
	v_mov_b32_e32 v40, 0
	v_mov_b32_e32 v41, 0
	v_mov_b32_e32 v42, 0
	v_mov_b32_e32 v43, 0
	v_mov_b32_e32 v44, 0
	v_mov_b32_e32 v45, 0
	v_mov_b32_e32 v46, 0
	v_mov_b32_e32 v47, 0
	v_mov_b32_e32 v48, 0
	v_mov_b32_e32 v49, 0
	v_mov_b32_e32 v50, 0
	v_mov_b32_e32 v51, 0
	v_mov_b32_e32 v52, 0
	v_mov_b32_e32 v53, 0
	v_mov_b32_e32 v54, 0
	v_mov_b32_e32 v55, 0
	v_mov_b32_e32 v56, 0
	v_mov_b32_e32 v57, 0
	v_mov_b32_e32 v58, 0
	v_mov_b32_e32 v59, 0
	v_mov_b32_e32 v60, 0
	v_mov_b32_e32 v61, 0
	v_mov_b32_e32 v62, 0
	v_mov_b32_e32 v63, 0
	v_mov_b32_e32 v64, 0
	v_mov_b32_e32 v65, 0
	v_mov_b32_e32 v66, 0
	v_mov_b32_e32 v67, 0
	v_mov_b32_e32 v68, 0
	v_mov_b32_e32 v69, 0
	v_mov_b32_e32 v70, 0
	v_mov_b32_e32 v71, 0
	v_mov_b32_e32 v72, 0
	v_mov_b32_e32 v73, 0
	v_mov_b32_e32 v74, 0
	v_mov_b32_e32 v75, 0
	v_mov_b32_e32 v76, 0
	v_mov_b32_e32 v77, 0
	v_mov_b32_e32 v78, 0
	v_mov_b32_e32 v79, 0
	v_mov_b32_e32 v80, 0
	v_mov_b32_e32 v81, 0
	v_mov_b32_e32 v82, 0
	v_mov_b32_e32 v83, 0
	v_mov_b32_e32 v84, 0
	v_mov_b32_e32 v85, 0
	v_mov_b32_e32 v86, 0
	v_mov_b32_e32 v87, 0
	v_mov_b32_e32 v88, 0
	v_mov_b32_e32 v89, 0
	v_mov_b32_e32 v90, 0
	v_mov_b32_e32 v91, 0
	v_mov_b32_e32 v92, 0
	v_mov_b32_e32 v93, 0
	v_mov_b32_e32 v94, 0
	v_mov_b32_e32 v95, 0
	v_mov_b32_e32 v96, 0
	v_mov_b32_e32 v97, 0
	v_mov_b32_e32 v98, 0
	v_mov_b32_e32 v99, 0
	v_mov_b32_e32 v100, 0
	v_mov_b32_e32 v101, 0
	v_mov_b32_e32 v102, 0
	v_mov_b32_e32 v103, 0
	v_mov_b32_e32 v104, 0
	v_mov_b32_e32 v105, 0
	v_mov_b32_e32 v106, 0
	v_mov_b32_e32 v107, 0
	v_mov_b32_e32 v108, 0
	v_mov_b32_e32 v109, 0
	v_mov_b32_e32 v110, 0
	v_mov_b32_e32 v111, 0
	v_mov_b32_e32 v112, 0
	v_mov_b32_e32 v113, 0
	v_mov_b32_e32 v114, 0
	v_mov_b32_e32 v115, 0
	v_mov_b32_e32 v116, 0
	v_mov_b32_e32 v117, 0
	v_mov_b32_e32 v118, 0
	v_mov_b32_e32 v119, 0
	v_mov_b32_e32 v120, 0
	v_mov_b32_e32 v121, 0
	v_mov_b32_e32 v122, 0
	v_mov_b32_e32 v123, 0
	v_mov_b32_e32 v124, 0
	v_mov_b32_e32 v125, 0
	v_mov_b32_e32 v126, 0
	v_mov_b32_e32 v127, 0
	v_mov_b32_e32 v128, 0
	v_mov_b32_e32 v129, 0
	s_waitcnt vmcnt(12)
	s_barrier
	ds_read_b128 v[130:133], v154 offset:16
	ds_read_b128 v[138:141], v156 offset:8208
	ds_read_b128 v[142:145], v156 offset:10256
	ds_read_b128 v[134:137], v154 offset:2064
	ds_read_b128 v[146:149], v158 offset:8208
	ds_read_b128 v[150:153], v158 offset:10256
	s_mov_b32 s59, 9

.Lhw_ffnup_sloop:
	s_sub_i32 s62, 0x108, s64
	s_lshl_b32 s62, s62, 1
	s_cmp_ge_u32 s2, s62
	s_cbranch_scc1 .Lhw_ffnup_exit
	s_lshr_b32 s63, s2, 1
	s_add_i32 s63, s63, s64
	s_mul_i32 s14, s63, 5462
	s_lshr_b32 s14, s14, 16
	s_mul_i32 s6, s14, 12
	s_sub_i32 s6, s63, s6
	v_readlane_b32 s13, v246, 16
	s_nop 0
	s_add_i32 s6, s6, s13
	s_lshl_b32 s6, s6, 7
	s_lshl_b32 s14, s14, 8
	s_and_b32 s12, s2, 1
	s_lshl_b32 s12, s12, 7
	s_add_i32 s14, s14, s12
	s_lshl_b32 vcc_lo, s6, 11
	s_add_u32 s66, s10, vcc_lo
	s_addc_u32 s67, s11, 0
	s_lshl_b32 vcc_lo, s14, 11
	s_add_u32 s12, s0, vcc_lo
	s_addc_u32 s13, s1, 0
	s_barrier
	s_add_u32 m0, s65, 0x0
	s_nop 0
	global_load_lds_dwordx4 v160, s[66:67]
	s_add_u32 m0, s65, 0x1000
	s_nop 0
	global_load_lds_dwordx4 v161, s[66:67]
	s_add_u32 m0, s65, 0x2000
	s_nop 0
	global_load_lds_dwordx4 v160, s[12:13]
	s_add_u32 m0, s65, 0x3000
	s_nop 0
	global_load_lds_dwordx4 v161, s[12:13]
	s_add_u32 s66, s66, 64
	s_addc_u32 s67, s67, 0
	s_add_u32 s12, s12, 64
	s_addc_u32 s13, s13, 0
	s_add_u32 m0, s65, 0x6000
	s_nop 0
	global_load_lds_dwordx4 v160, s[66:67]
	s_add_u32 m0, s65, 0x7000
	s_nop 0
	global_load_lds_dwordx4 v161, s[66:67]
	s_add_u32 m0, s65, 0x8000
	s_nop 0
	global_load_lds_dwordx4 v160, s[12:13]
	s_add_u32 m0, s65, 0x9000
	s_nop 0
	global_load_lds_dwordx4 v161, s[12:13]
	s_add_u32 s66, s66, 64
	s_addc_u32 s67, s67, 0
	s_add_u32 s12, s12, 64
	s_addc_u32 s13, s13, 0
	s_add_u32 m0, s65, 0xc000
	s_nop 0
	global_load_lds_dwordx4 v160, s[66:67]
	s_add_u32 m0, s65, 0xd000
	s_nop 0
	global_load_lds_dwordx4 v161, s[66:67]
	s_add_u32 m0, s65, 0xe000
	s_nop 0
	global_load_lds_dwordx4 v160, s[12:13]
	s_add_u32 m0, s65, 0xf000
	s_nop 0
	global_load_lds_dwordx4 v161, s[12:13]
	s_add_u32 s66, s66, 64
	s_addc_u32 s67, s67, 0
	s_add_u32 s12, s12, 64
	s_addc_u32 s13, s13, 0
	v_mov_b32_e32 v2, 0
	v_mov_b32_e32 v3, 0
	v_mov_b32_e32 v4, 0
	v_mov_b32_e32 v5, 0
	v_mov_b32_e32 v6, 0
	v_mov_b32_e32 v7, 0
	v_mov_b32_e32 v8, 0
	v_mov_b32_e32 v9, 0
	v_mov_b32_e32 v10, 0
	v_mov_b32_e32 v11, 0
	v_mov_b32_e32 v12, 0
	v_mov_b32_e32 v13, 0
	v_mov_b32_e32 v14, 0
	v_mov_b32_e32 v15, 0
	v_mov_b32_e32 v16, 0
	v_mov_b32_e32 v17, 0
	v_mov_b32_e32 v18, 0
	v_mov_b32_e32 v19, 0
	v_mov_b32_e32 v20, 0
	v_mov_b32_e32 v21, 0
	v_mov_b32_e32 v22, 0
	v_mov_b32_e32 v23, 0
	v_mov_b32_e32 v24, 0
	v_mov_b32_e32 v25, 0
	v_mov_b32_e32 v26, 0
	v_mov_b32_e32 v27, 0
	v_mov_b32_e32 v28, 0
	v_mov_b32_e32 v29, 0
	v_mov_b32_e32 v30, 0
	v_mov_b32_e32 v31, 0
	v_mov_b32_e32 v32, 0
	v_mov_b32_e32 v33, 0
	v_mov_b32_e32 v34, 0
	v_mov_b32_e32 v35, 0
	v_mov_b32_e32 v36, 0
	v_mov_b32_e32 v37, 0
	v_mov_b32_e32 v38, 0
	v_mov_b32_e32 v39, 0
	v_mov_b32_e32 v40, 0
	v_mov_b32_e32 v41, 0
	v_mov_b32_e32 v42, 0
	v_mov_b32_e32 v43, 0
	v_mov_b32_e32 v44, 0
	v_mov_b32_e32 v45, 0
	v_mov_b32_e32 v46, 0
	v_mov_b32_e32 v47, 0
	v_mov_b32_e32 v48, 0
	v_mov_b32_e32 v49, 0
	v_mov_b32_e32 v50, 0
	v_mov_b32_e32 v51, 0
	v_mov_b32_e32 v52, 0
	v_mov_b32_e32 v53, 0
	v_mov_b32_e32 v54, 0
	v_mov_b32_e32 v55, 0
	v_mov_b32_e32 v56, 0
	v_mov_b32_e32 v57, 0
	v_mov_b32_e32 v58, 0
	v_mov_b32_e32 v59, 0
	v_mov_b32_e32 v60, 0
	v_mov_b32_e32 v61, 0
	v_mov_b32_e32 v62, 0
	v_mov_b32_e32 v63, 0
	v_mov_b32_e32 v64, 0
	v_mov_b32_e32 v65, 0
	s_waitcnt vmcnt(8)
	s_barrier
	ds_read_b128 v[130:133], v154 offset:16
	ds_read_b128 v[138:141], v156 offset:8208
	ds_read_b128 v[142:145], v156 offset:10256
	ds_read_b128 v[134:137], v154 offset:2064
	s_mov_b32 s59, 9
